# attention steps: the 36 hazard-free s_nop slots left by the row-max/row-sum trims removed
# speedup vs baseline: 1.0015x; 1.0015x over previous
.LBB0_498:
	v_add_u32_e32 v208, s6, v220
	ds_read_b64_tr_b16 v[194:195], v208 offset:24576
	ds_read_b64_tr_b16 v[196:197], v208 offset:25088
	s_waitcnt lgkmcnt(9)
	v_mfma_f32_32x32x16_bf16 v[114:129], v[190:193], v[150:153], v[50:65]
	v_add_f32_e32 v98, v82, v83
	v_add_f32_e32 v98, v84, v98
	v_add_f32_e32 v98, v85, v98
	v_add_f32_e32 v98, v86, v98
	v_add_f32_e32 v98, v87, v98
	v_cvt_pk_bf16_f32 v158, v82, v83
	v_cvt_pk_bf16_f32 v159, v84, v85
	ds_read_b64_tr_b16 v[190:191], v208 offset:28672
	ds_read_b64_tr_b16 v[192:193], v208 offset:29184
	v_add_f32_e32 v82, v88, v98
	s_waitcnt lgkmcnt(10)
	v_mfma_f32_32x32x16_bf16 v[98:113], v[186:189], v[150:153], v[50:65]
	v_add_f32_e32 v82, v89, v82
	v_add_f32_e32 v82, v90, v82
	v_add_f32_e32 v82, v91, v82
	v_cvt_pk_bf16_f32 v160, v86, v87
	v_cvt_pk_bf16_f32 v161, v88, v89
	ds_read_b64_tr_b16 v[186:187], v208 offset:25600
	ds_read_b64_tr_b16 v[188:189], v208 offset:26112
	s_waitcnt lgkmcnt(11)
	v_mfma_f32_32x32x16_bf16 v[114:129], v[182:185], v[142:145], v[114:129]
	v_add_f32_e32 v82, v92, v82
	v_add_f32_e32 v82, v93, v82
	v_add_f32_e32 v82, v94, v82
	v_add_f32_e32 v82, v95, v82
	v_cvt_pk_bf16_f32 v154, v90, v91
	v_cvt_pk_bf16_f32 v155, v92, v93
	ds_read_b64_tr_b16 v[90:91], v208 offset:29696
	ds_read_b64_tr_b16 v[92:93], v208 offset:30208
	s_waitcnt lgkmcnt(12)
	v_mfma_f32_32x32x16_bf16 v[98:113], v[178:181], v[142:145], v[98:113]
	v_add_f32_e32 v82, v96, v82
	v_add_f32_e32 v82, v97, v82
	v_add_f32_e32 v82, v66, v82
	v_add_f32_e32 v82, v67, v82
	v_cvt_pk_bf16_f32 v156, v94, v95
	v_cvt_pk_bf16_f32 v157, v96, v97
	ds_read_b64_tr_b16 v[86:87], v208 offset:26624
	ds_read_b64_tr_b16 v[88:89], v208 offset:27136
	s_waitcnt lgkmcnt(13)
	v_mfma_f32_32x32x16_bf16 v[114:129], v[174:177], v[134:137], v[114:129]
	v_add_f32_e32 v82, v68, v82
	v_add_f32_e32 v82, v69, v82
	v_add_f32_e32 v82, v70, v82
	v_add_f32_e32 v94, v71, v82
	v_cvt_pk_bf16_f32 v146, v66, v67
	v_cvt_pk_bf16_f32 v147, v68, v69
	ds_read_b64_tr_b16 v[82:83], v208 offset:30720
	ds_read_b64_tr_b16 v[84:85], v208 offset:31232
	s_waitcnt lgkmcnt(14)
	v_mfma_f32_32x32x16_bf16 v[98:113], v[170:173], v[134:137], v[98:113]
	v_add_f32_e32 v66, v72, v94
	v_add_f32_e32 v66, v73, v66
	v_add_f32_e32 v66, v74, v66
	v_add_f32_e32 v66, v75, v66
	v_cvt_pk_bf16_f32 v148, v70, v71
	v_cvt_pk_bf16_f32 v149, v72, v73
	ds_read_b64_tr_b16 v[70:71], v208 offset:27648
	ds_read_b64_tr_b16 v[72:73], v208 offset:28160
	s_waitcnt lgkmcnt(14)
	v_mfma_f32_32x32x16_bf16 v[114:129], v[166:169], v[130:133], v[114:129]
	v_add_f32_e32 v66, v76, v66
	v_add_f32_e32 v66, v77, v66
	v_add_f32_e32 v66, v78, v66
	v_add_f32_e32 v94, v79, v66
	v_cvt_pk_bf16_f32 v138, v74, v75
	v_cvt_pk_bf16_f32 v139, v76, v77
	ds_read_b64_tr_b16 v[66:67], v208 offset:31744
	ds_read_b64_tr_b16 v[68:69], v208 offset:32256
	v_mfma_f32_32x32x16_bf16 v[98:113], v[162:165], v[130:133], v[98:113]
	v_add_f32_e32 v74, v80, v94
	v_add_f32_e32 v76, v81, v74
	v_cvt_pk_bf16_f32 v140, v78, v79
	v_cvt_pk_bf16_f32 v141, v80, v81
	v_lshl_add_u64 v[74:75], v[204:205], 0, s[68:69]
	s_add_i32 s3, s12, s49
	s_mov_b32 s6, m0
	s_mov_b32 m0, s3
	s_nop 0
	global_load_lds_dwordx4 v[74:75], off
	s_mov_b32 m0, s6
	v_lshl_add_u64 v[74:75], v[202:203], 0, s[68:69]
	s_add_i32 s3, s63, s61
	s_mov_b32 s6, m0
	s_mov_b32 m0, s3
	s_nop 0
	global_load_lds_dwordx4 v[74:75], off
	s_mov_b32 m0, s6
	s_nop 0
	s_nop 0
	v_max_f32_e32 v74, v114, v115
	v_max3_f32 v75, v116, v117, v99
	v_max3_f32 v74, v74, v98, v100
	v_max3_f32 v74, v74, v101, v118
	v_max3_f32 v75, v75, v120, v121
	v_max3_f32 v74, v74, v119, v102
	v_max3_f32 v75, v75, v104, v105
	v_max3_f32 v74, v74, v103, v122
	v_max3_f32 v75, v75, v124, v125
	v_max3_f32 v74, v74, v123, v106
	v_max3_f32 v75, v75, v108, v109
	v_max3_f32 v74, v74, v107, v126
	v_max3_f32 v75, v75, v128, v129
	v_max3_f32 v74, v74, v127, v110
	v_max3_f32 v75, v75, v112, v113
	v_max3_f32 v74, v74, v111, v75
	v_mov_b32_e32 v75, v74
	s_nop 1
	v_permlane32_swap_b32_e32 v74, v75
	v_max_f32_e32 v74, v74, v75
	v_cmp_lt_f32_e32 vcc, s33, v74
	s_cmp_lg_u64 vcc, 0
	v_add_f32_e32 v208, v222, v76
	s_cselect_b64 s[6:7], -1, 0
	s_cbranch_vccnz .LBB0_506

.LBB0_501:
	s_add_i32 s3, s63, 0x2000
	s_cmpk_lg_i32 s63, 0x4000
	s_cselect_b32 s62, s3, 0
	v_add_u32_e32 v210, s12, v220
	ds_read_b64_tr_b16 v[170:171], v210 offset:24576
	ds_read_b64_tr_b16 v[172:173], v210 offset:25088
	s_waitcnt lgkmcnt(9)
	v_mfma_f32_32x32x16_bf16 v[82:97], v[74:77], v[150:153], v[50:65]
	v_add_f32_e32 v66, v114, v115
	v_add_f32_e32 v66, v116, v66
	v_add_f32_e32 v66, v117, v66
	v_add_f32_e32 v66, v118, v66
	v_add_f32_e32 v66, v119, v66
	v_cvt_pk_bf16_f32 v158, v114, v115
	v_cvt_pk_bf16_f32 v159, v116, v117
	ds_read_b64_tr_b16 v[166:167], v210 offset:28672
	ds_read_b64_tr_b16 v[168:169], v210 offset:29184
	v_add_f32_e32 v66, v120, v66
	v_add_f32_e32 v66, v121, v66
	v_add_f32_e32 v66, v122, v66
	v_add_f32_e32 v114, v123, v66
	s_waitcnt lgkmcnt(10)
	v_mfma_f32_32x32x16_bf16 v[66:81], v[162:165], v[150:153], v[50:65]
	v_cvt_pk_bf16_f32 v160, v118, v119
	v_cvt_pk_bf16_f32 v161, v120, v121
	ds_read_b64_tr_b16 v[162:163], v210 offset:25600
	ds_read_b64_tr_b16 v[164:165], v210 offset:26112
	s_waitcnt lgkmcnt(11)
	v_mfma_f32_32x32x16_bf16 v[82:97], v[194:197], v[142:145], v[82:97]
	v_add_f32_e32 v114, v124, v114
	v_add_f32_e32 v114, v125, v114
	v_add_f32_e32 v114, v126, v114
	v_add_f32_e32 v114, v127, v114
	v_cvt_pk_bf16_f32 v154, v122, v123
	v_cvt_pk_bf16_f32 v155, v124, v125
	ds_read_b64_tr_b16 v[122:123], v210 offset:29696
	ds_read_b64_tr_b16 v[124:125], v210 offset:30208
	s_waitcnt lgkmcnt(12)
	v_mfma_f32_32x32x16_bf16 v[66:81], v[186:189], v[142:145], v[66:81]
	v_add_f32_e32 v114, v128, v114
	v_add_f32_e32 v114, v129, v114
	v_add_f32_e32 v114, v98, v114
	v_add_f32_e32 v114, v99, v114
	v_cvt_pk_bf16_f32 v156, v126, v127
	v_cvt_pk_bf16_f32 v157, v128, v129
	ds_read_b64_tr_b16 v[118:119], v210 offset:26624
	ds_read_b64_tr_b16 v[120:121], v210 offset:27136
	s_waitcnt lgkmcnt(13)
	v_mfma_f32_32x32x16_bf16 v[82:97], v[190:193], v[134:137], v[82:97]
	v_add_f32_e32 v114, v100, v114
	v_add_f32_e32 v114, v101, v114
	v_add_f32_e32 v114, v102, v114
	v_add_f32_e32 v126, v103, v114
	v_cvt_pk_bf16_f32 v146, v98, v99
	v_cvt_pk_bf16_f32 v147, v100, v101
	ds_read_b64_tr_b16 v[114:115], v210 offset:30720
	ds_read_b64_tr_b16 v[116:117], v210 offset:31232
	s_waitcnt lgkmcnt(14)
	v_mfma_f32_32x32x16_bf16 v[66:81], v[178:181], v[134:137], v[66:81]
	v_add_f32_e32 v98, v104, v126
	v_add_f32_e32 v98, v105, v98
	v_add_f32_e32 v98, v106, v98
	v_add_f32_e32 v98, v107, v98
	v_cvt_pk_bf16_f32 v148, v102, v103
	v_cvt_pk_bf16_f32 v149, v104, v105
	ds_read_b64_tr_b16 v[102:103], v210 offset:27648
	ds_read_b64_tr_b16 v[104:105], v210 offset:28160
	s_waitcnt lgkmcnt(14)
	v_mfma_f32_32x32x16_bf16 v[82:97], v[182:185], v[130:133], v[82:97]
	v_add_f32_e32 v98, v108, v98
	v_add_f32_e32 v98, v109, v98
	v_add_f32_e32 v98, v110, v98
	v_add_f32_e32 v126, v111, v98
	v_cvt_pk_bf16_f32 v138, v106, v107
	v_cvt_pk_bf16_f32 v139, v108, v109
	ds_read_b64_tr_b16 v[98:99], v210 offset:31744
	ds_read_b64_tr_b16 v[100:101], v210 offset:32256
	v_mfma_f32_32x32x16_bf16 v[66:81], v[174:177], v[130:133], v[66:81]
	v_add_f32_e32 v106, v112, v126
	v_add_f32_e32 v106, v113, v106
	v_cvt_pk_bf16_f32 v140, v110, v111
	v_cvt_pk_bf16_f32 v141, v112, v113
	s_nop 0
	s_nop 0
	v_max_f32_e32 v107, v82, v83
	s_nop 3
	v_max3_f32 v108, v84, v85, v67
	v_max3_f32 v107, v107, v66, v68
	v_max3_f32 v107, v107, v69, v86
	v_max3_f32 v108, v108, v88, v89
	v_max3_f32 v107, v107, v87, v70
	v_max3_f32 v108, v108, v72, v73
	v_max3_f32 v107, v107, v71, v90
	v_max3_f32 v108, v108, v92, v93
	v_max3_f32 v107, v107, v91, v74
	v_max3_f32 v108, v108, v76, v77
	v_max3_f32 v107, v107, v75, v94
	v_max3_f32 v108, v108, v96, v97
	v_max3_f32 v107, v107, v95, v78
	v_max3_f32 v108, v108, v80, v81
	v_add_f32_e32 v222, v208, v106
	v_max3_f32 v106, v107, v79, v108
	v_mov_b32_e32 v107, v106
	s_nop 1
	v_permlane32_swap_b32_e32 v106, v107
	s_add_i32 s3, s63, s49
	s_mov_b32 s6, m0
	s_mov_b32 m0, s3
	s_nop 0
	global_load_lds_dwordx4 v[204:205], off
	s_mov_b32 m0, s6
	v_max_f32_e32 v106, v106, v107
	s_add_i32 s3, s62, s61
	s_mov_b32 s6, m0
	s_mov_b32 m0, s3
	s_nop 0
	global_load_lds_dwordx4 v[202:203], off
	s_mov_b32 m0, s6
	v_cmp_lt_f32_e32 vcc, s33, v106
	s_cmp_lg_u64 vcc, 0
	s_cselect_b64 s[6:7], -1, 0
	s_cbranch_vccnz .LBB0_509

.LBB0_514:
	v_add_u32_e32 v194, s66, v220
	ds_read_b64_tr_b16 v[126:127], v194 offset:24576
	ds_read_b64_tr_b16 v[128:129], v194 offset:25088
	v_add_f32_e32 v98, v82, v83
	v_add_f32_e32 v98, v84, v98
	v_add_f32_e32 v98, v85, v98
	v_add_f32_e32 v98, v86, v98
	v_add_f32_e32 v114, v87, v98
	s_waitcnt lgkmcnt(9)
	v_mfma_f32_32x32x16_bf16 v[98:113], v[190:193], v[150:153], v[50:65]
	v_cvt_pk_bf16_f32 v158, v82, v83
	v_cvt_pk_bf16_f32 v159, v84, v85
	ds_read_b64_tr_b16 v[122:123], v194 offset:28672
	ds_read_b64_tr_b16 v[124:125], v194 offset:29184
	s_waitcnt lgkmcnt(10)
	v_mfma_f32_32x32x16_bf16 v[50:65], v[186:189], v[150:153], v[50:65]
	v_add_f32_e32 v82, v88, v114
	v_add_f32_e32 v82, v89, v82
	v_add_f32_e32 v82, v90, v82
	v_add_f32_e32 v82, v91, v82
	v_cvt_pk_bf16_f32 v160, v86, v87
	v_cvt_pk_bf16_f32 v161, v88, v89
	ds_read_b64_tr_b16 v[118:119], v194 offset:25600
	ds_read_b64_tr_b16 v[120:121], v194 offset:26112
	s_waitcnt lgkmcnt(11)
	v_mfma_f32_32x32x16_bf16 v[98:113], v[182:185], v[142:145], v[98:113]
	v_add_f32_e32 v82, v92, v82
	v_add_f32_e32 v82, v93, v82
	v_add_f32_e32 v82, v94, v82
	v_add_f32_e32 v82, v95, v82
	v_cvt_pk_bf16_f32 v154, v90, v91
	v_cvt_pk_bf16_f32 v155, v92, v93
	ds_read_b64_tr_b16 v[114:115], v194 offset:29696
	ds_read_b64_tr_b16 v[116:117], v194 offset:30208
	s_waitcnt lgkmcnt(12)
	v_mfma_f32_32x32x16_bf16 v[50:65], v[178:181], v[142:145], v[50:65]
	v_add_f32_e32 v82, v96, v82
	v_add_f32_e32 v82, v97, v82
	v_add_f32_e32 v82, v66, v82
	v_add_f32_e32 v82, v67, v82
	v_cvt_pk_bf16_f32 v156, v94, v95
	v_cvt_pk_bf16_f32 v157, v96, v97
	ds_read_b64_tr_b16 v[94:95], v194 offset:26624
	ds_read_b64_tr_b16 v[96:97], v194 offset:27136
	s_waitcnt lgkmcnt(13)
	v_mfma_f32_32x32x16_bf16 v[98:113], v[174:177], v[134:137], v[98:113]
	v_add_f32_e32 v82, v68, v82
	v_add_f32_e32 v82, v69, v82
	v_add_f32_e32 v82, v70, v82
	v_add_f32_e32 v82, v71, v82
	v_cvt_pk_bf16_f32 v146, v66, v67
	v_cvt_pk_bf16_f32 v147, v68, v69
	ds_read_b64_tr_b16 v[90:91], v194 offset:30720
	ds_read_b64_tr_b16 v[92:93], v194 offset:31232
	s_waitcnt lgkmcnt(14)
	v_mfma_f32_32x32x16_bf16 v[50:65], v[170:173], v[134:137], v[50:65]
	v_add_f32_e32 v66, v72, v82
	v_add_f32_e32 v66, v73, v66
	v_add_f32_e32 v66, v74, v66
	v_add_f32_e32 v66, v75, v66
	v_cvt_pk_bf16_f32 v148, v70, v71
	v_cvt_pk_bf16_f32 v149, v72, v73
	ds_read_b64_tr_b16 v[86:87], v194 offset:27648
	ds_read_b64_tr_b16 v[88:89], v194 offset:28160
	s_waitcnt lgkmcnt(14)
	v_mfma_f32_32x32x16_bf16 v[98:113], v[166:169], v[130:133], v[98:113]
	v_add_f32_e32 v66, v76, v66
	v_add_f32_e32 v66, v77, v66
	v_add_f32_e32 v66, v78, v66
	v_add_f32_e32 v66, v79, v66
	v_cvt_pk_bf16_f32 v138, v74, v75
	v_cvt_pk_bf16_f32 v139, v76, v77
	ds_read_b64_tr_b16 v[82:83], v194 offset:31744
	ds_read_b64_tr_b16 v[84:85], v194 offset:32256
	v_mfma_f32_32x32x16_bf16 v[50:65], v[162:165], v[130:133], v[50:65]
	v_add_f32_e32 v66, v80, v66
	v_add_f32_e32 v66, v81, v66
	v_cvt_pk_bf16_f32 v140, v78, v79
	v_cvt_pk_bf16_f32 v141, v80, v81
	s_nop 0
	s_nop 0
	v_max_f32_e32 v67, v98, v99
	s_nop 3
	v_max3_f32 v68, v100, v101, v51
	v_max3_f32 v67, v67, v50, v52
	v_max3_f32 v67, v67, v53, v102
	v_max3_f32 v68, v68, v104, v105
	v_max3_f32 v67, v67, v103, v54
	v_max3_f32 v68, v68, v56, v57
	v_max3_f32 v67, v67, v55, v106
	v_max3_f32 v68, v68, v108, v109
	v_max3_f32 v67, v67, v107, v58
	v_max3_f32 v68, v68, v60, v61
	v_max3_f32 v67, v67, v59, v110
	v_max3_f32 v68, v68, v112, v113
	v_max3_f32 v67, v67, v111, v62
	v_max3_f32 v68, v68, v64, v65
	v_add_f32_e32 v130, v222, v66
	v_max3_f32 v66, v67, v63, v68
	v_mov_b32_e32 v67, v66
	s_nop 1
	v_permlane32_swap_b32_e32 v66, v67
	v_max_f32_e32 v66, v66, v67
	v_cmp_lt_f32_e32 vcc, s33, v66
	s_cmp_lg_u64 vcc, 0
	s_cselect_b64 s[0:1], -1, 0
	s_cbranch_vccnz .LBB0_565

.LBB0_521:
	v_add_u32_e32 v202, s63, v220
	ds_read_b64_tr_b16 v[198:199], v202 offset:24576
	ds_read_b64_tr_b16 v[200:201], v202 offset:25088
	s_waitcnt lgkmcnt(9)
	v_mfma_f32_32x32x16_bf16 v[114:129], v[190:193], v[150:153], v[50:65]
	v_add_f32_e32 v98, v82, v83
	v_add_f32_e32 v98, v84, v98
	v_add_f32_e32 v98, v85, v98
	v_add_f32_e32 v98, v86, v98
	v_add_f32_e32 v98, v87, v98
	v_cvt_pk_bf16_f32 v158, v82, v83
	v_cvt_pk_bf16_f32 v159, v84, v85
	ds_read_b64_tr_b16 v[190:191], v202 offset:28672
	ds_read_b64_tr_b16 v[192:193], v202 offset:29184
	v_add_f32_e32 v82, v88, v98
	s_waitcnt lgkmcnt(10)
	v_mfma_f32_32x32x16_bf16 v[98:113], v[186:189], v[150:153], v[50:65]
	v_add_f32_e32 v82, v89, v82
	v_add_f32_e32 v82, v90, v82
	v_add_f32_e32 v82, v91, v82
	v_cvt_pk_bf16_f32 v160, v86, v87
	v_cvt_pk_bf16_f32 v161, v88, v89
	ds_read_b64_tr_b16 v[194:195], v202 offset:25600
	ds_read_b64_tr_b16 v[196:197], v202 offset:26112
	s_waitcnt lgkmcnt(11)
	v_mfma_f32_32x32x16_bf16 v[114:129], v[182:185], v[142:145], v[114:129]
	v_add_f32_e32 v82, v92, v82
	v_add_f32_e32 v82, v93, v82
	v_add_f32_e32 v82, v94, v82
	v_add_f32_e32 v82, v95, v82
	v_cvt_pk_bf16_f32 v154, v90, v91
	v_cvt_pk_bf16_f32 v155, v92, v93
	ds_read_b64_tr_b16 v[90:91], v202 offset:29696
	ds_read_b64_tr_b16 v[92:93], v202 offset:30208
	s_waitcnt lgkmcnt(12)
	v_mfma_f32_32x32x16_bf16 v[98:113], v[178:181], v[142:145], v[98:113]
	v_add_f32_e32 v82, v96, v82
	v_add_f32_e32 v82, v97, v82
	v_add_f32_e32 v82, v66, v82
	v_add_f32_e32 v82, v67, v82
	v_cvt_pk_bf16_f32 v156, v94, v95
	v_cvt_pk_bf16_f32 v157, v96, v97
	ds_read_b64_tr_b16 v[86:87], v202 offset:26624
	ds_read_b64_tr_b16 v[88:89], v202 offset:27136
	s_waitcnt lgkmcnt(13)
	v_mfma_f32_32x32x16_bf16 v[114:129], v[174:177], v[134:137], v[114:129]
	v_add_f32_e32 v82, v68, v82
	v_add_f32_e32 v82, v69, v82
	v_add_f32_e32 v82, v70, v82
	v_add_f32_e32 v94, v71, v82
	v_cvt_pk_bf16_f32 v146, v66, v67
	v_cvt_pk_bf16_f32 v147, v68, v69
	ds_read_b64_tr_b16 v[82:83], v202 offset:30720
	ds_read_b64_tr_b16 v[84:85], v202 offset:31232
	s_waitcnt lgkmcnt(14)
	v_mfma_f32_32x32x16_bf16 v[98:113], v[170:173], v[134:137], v[98:113]
	v_add_f32_e32 v66, v72, v94
	v_add_f32_e32 v66, v73, v66
	v_add_f32_e32 v66, v74, v66
	v_add_f32_e32 v66, v75, v66
	v_cvt_pk_bf16_f32 v148, v70, v71
	v_cvt_pk_bf16_f32 v149, v72, v73
	ds_read_b64_tr_b16 v[70:71], v202 offset:27648
	ds_read_b64_tr_b16 v[72:73], v202 offset:28160
	s_waitcnt lgkmcnt(14)
	v_mfma_f32_32x32x16_bf16 v[114:129], v[166:169], v[130:133], v[114:129]
	v_add_f32_e32 v66, v76, v66
	v_add_f32_e32 v66, v77, v66
	v_add_f32_e32 v66, v78, v66
	v_add_f32_e32 v94, v79, v66
	v_cvt_pk_bf16_f32 v138, v74, v75
	v_cvt_pk_bf16_f32 v139, v76, v77
	ds_read_b64_tr_b16 v[66:67], v202 offset:31744
	ds_read_b64_tr_b16 v[68:69], v202 offset:32256
	v_mfma_f32_32x32x16_bf16 v[98:113], v[162:165], v[130:133], v[98:113]
	v_add_f32_e32 v74, v80, v94
	v_add_f32_e32 v74, v81, v74
	v_cvt_pk_bf16_f32 v140, v78, v79
	v_cvt_pk_bf16_f32 v141, v80, v81
	s_add_i32 s0, s8, 1
	s_cmp_ge_u32 s0, s48
	s_cselect_b64 s[72:73], -1, 0
	s_and_b64 vcc, exec, s[72:73]
	s_cbranch_vccnz .LBB0_523
	s_add_i32 s0, s62, s49
	v_lshl_add_u64 v[76:77], v[210:211], 0, s[68:69]
	s_mov_b32 s1, m0
	s_mov_b32 m0, s0
	s_nop 0
	global_load_lds_dwordx4 v[76:77], off
	s_mov_b32 m0, s1
.LBB0_523:
	v_add_f32_e32 v222, v222, v74
	s_nop 0
	s_nop 0
	v_max_f32_e32 v74, v114, v115
	v_max3_f32 v75, v116, v117, v99
	v_max3_f32 v74, v74, v98, v100
	v_max3_f32 v74, v74, v101, v118
	v_max3_f32 v75, v75, v120, v121
	v_max3_f32 v74, v74, v119, v102
	v_max3_f32 v75, v75, v104, v105
	v_max3_f32 v74, v74, v103, v122
	v_max3_f32 v75, v75, v124, v125
	v_max3_f32 v74, v74, v123, v106
	v_max3_f32 v75, v75, v108, v109
	v_max3_f32 v74, v74, v107, v126
	v_max3_f32 v75, v75, v128, v129
	v_max3_f32 v74, v74, v127, v110
	v_max3_f32 v75, v75, v112, v113
	v_max3_f32 v74, v74, v111, v75
	v_mov_b32_e32 v75, v74
	s_nop 1
	v_permlane32_swap_b32_e32 v74, v75
	v_max_f32_e32 v74, v74, v75
	s_add_i32 s0, s66, s61
	s_mov_b32 s1, m0
	s_mov_b32 m0, s0
	s_nop 0
	global_load_lds_dwordx4 v[208:209], off
	s_mov_b32 m0, s1
	v_cmp_lt_f32_e32 vcc, s33, v74
	s_cmp_lg_u64 vcc, 0
	s_cselect_b64 s[0:1], -1, 0
	s_cbranch_vccnz .LBB0_559

.LBB0_528:
	v_add_u32_e32 v224, s62, v220
	ds_read_b64_tr_b16 v[202:203], v224 offset:24576
	ds_read_b64_tr_b16 v[204:205], v224 offset:25088
	s_waitcnt lgkmcnt(9)
	v_mfma_f32_32x32x16_bf16 v[82:97], v[190:193], v[150:153], v[50:65]
	v_add_f32_e32 v66, v114, v115
	v_add_f32_e32 v66, v116, v66
	v_add_f32_e32 v66, v117, v66
	v_add_f32_e32 v66, v118, v66
	v_add_f32_e32 v66, v119, v66
	v_cvt_pk_bf16_f32 v158, v114, v115
	v_cvt_pk_bf16_f32 v159, v116, v117
	ds_read_b64_tr_b16 v[198:199], v224 offset:28672
	ds_read_b64_tr_b16 v[200:201], v224 offset:29184
	v_add_f32_e32 v66, v120, v66
	v_add_f32_e32 v66, v121, v66
	v_add_f32_e32 v66, v122, v66
	v_add_f32_e32 v114, v123, v66
	s_waitcnt lgkmcnt(10)
	v_mfma_f32_32x32x16_bf16 v[66:81], v[186:189], v[150:153], v[50:65]
	v_cvt_pk_bf16_f32 v160, v118, v119
	v_cvt_pk_bf16_f32 v161, v120, v121
	ds_read_b64_tr_b16 v[194:195], v224 offset:25600
	ds_read_b64_tr_b16 v[196:197], v224 offset:26112
	s_waitcnt lgkmcnt(11)
	v_mfma_f32_32x32x16_bf16 v[82:97], v[182:185], v[142:145], v[82:97]
	v_add_f32_e32 v114, v124, v114
	v_add_f32_e32 v114, v125, v114
	v_add_f32_e32 v114, v126, v114
	v_add_f32_e32 v114, v127, v114
	v_cvt_pk_bf16_f32 v154, v122, v123
	v_cvt_pk_bf16_f32 v155, v124, v125
	ds_read_b64_tr_b16 v[122:123], v224 offset:29696
	ds_read_b64_tr_b16 v[124:125], v224 offset:30208
	s_waitcnt lgkmcnt(12)
	v_mfma_f32_32x32x16_bf16 v[66:81], v[178:181], v[142:145], v[66:81]
	v_add_f32_e32 v114, v128, v114
	v_add_f32_e32 v114, v129, v114
	v_add_f32_e32 v114, v98, v114
	v_add_f32_e32 v114, v99, v114
	v_cvt_pk_bf16_f32 v156, v126, v127
	v_cvt_pk_bf16_f32 v157, v128, v129
	ds_read_b64_tr_b16 v[118:119], v224 offset:26624
	ds_read_b64_tr_b16 v[120:121], v224 offset:27136
	s_waitcnt lgkmcnt(13)
	v_mfma_f32_32x32x16_bf16 v[82:97], v[174:177], v[134:137], v[82:97]
	v_add_f32_e32 v114, v100, v114
	v_add_f32_e32 v114, v101, v114
	v_add_f32_e32 v114, v102, v114
	v_add_f32_e32 v126, v103, v114
	v_cvt_pk_bf16_f32 v146, v98, v99
	v_cvt_pk_bf16_f32 v147, v100, v101
	ds_read_b64_tr_b16 v[114:115], v224 offset:30720
	ds_read_b64_tr_b16 v[116:117], v224 offset:31232
	s_waitcnt lgkmcnt(14)
	v_mfma_f32_32x32x16_bf16 v[66:81], v[170:173], v[134:137], v[66:81]
	v_add_f32_e32 v98, v104, v126
	v_add_f32_e32 v98, v105, v98
	v_add_f32_e32 v98, v106, v98
	v_add_f32_e32 v98, v107, v98
	v_cvt_pk_bf16_f32 v148, v102, v103
	v_cvt_pk_bf16_f32 v149, v104, v105
	ds_read_b64_tr_b16 v[102:103], v224 offset:27648
	ds_read_b64_tr_b16 v[104:105], v224 offset:28160
	s_waitcnt lgkmcnt(14)
	v_mfma_f32_32x32x16_bf16 v[82:97], v[166:169], v[130:133], v[82:97]
	v_add_f32_e32 v98, v108, v98
	v_add_f32_e32 v98, v109, v98
	v_add_f32_e32 v98, v110, v98
	v_add_f32_e32 v126, v111, v98
	v_cvt_pk_bf16_f32 v138, v106, v107
	v_cvt_pk_bf16_f32 v139, v108, v109
	ds_read_b64_tr_b16 v[98:99], v224 offset:31744
	ds_read_b64_tr_b16 v[100:101], v224 offset:32256
	v_mfma_f32_32x32x16_bf16 v[66:81], v[162:165], v[130:133], v[66:81]
	v_add_f32_e32 v106, v112, v126
	v_add_f32_e32 v106, v113, v106
	v_cvt_pk_bf16_f32 v140, v110, v111
	v_cvt_pk_bf16_f32 v141, v112, v113
	s_add_i32 s12, s8, 2
	s_cmp_ge_u32 s12, s48
	s_cselect_b64 s[74:75], -1, 0
	s_and_b64 vcc, exec, s[74:75]
	s_cbranch_vccnz .LBB0_530
	s_add_i32 s0, s66, s49
	s_mov_b32 s1, m0
	s_mov_b32 m0, s0
	s_nop 0
	global_load_lds_dwordx4 v[210:211], off
	s_mov_b32 m0, s1

.LBB0_532:
	v_add_f32_e32 v222, v222, v106
	s_nop 0
	s_nop 0
	v_max_f32_e32 v106, v82, v83
	v_max3_f32 v107, v84, v85, v67
	v_max3_f32 v106, v106, v66, v68
	v_max3_f32 v106, v106, v69, v86
	v_max3_f32 v107, v107, v88, v89
	v_max3_f32 v106, v106, v87, v70
	v_max3_f32 v107, v107, v72, v73
	v_max3_f32 v106, v106, v71, v90
	v_max3_f32 v107, v107, v92, v93
	v_max3_f32 v106, v106, v91, v74
	v_max3_f32 v107, v107, v76, v77
	v_max3_f32 v106, v106, v75, v94
	v_max3_f32 v107, v107, v96, v97
	v_max3_f32 v106, v106, v95, v78
	v_max3_f32 v107, v107, v80, v81
	v_max3_f32 v106, v106, v79, v107
	v_mov_b32_e32 v107, v106
	s_nop 1
	v_permlane32_swap_b32_e32 v106, v107
	v_max_f32_e32 v106, v106, v107
	v_cmp_lt_f32_e32 vcc, s33, v106
	s_cmp_lg_u64 vcc, 0
	s_cselect_b64 s[76:77], -1, 0
	s_cbranch_vccnz .LBB0_562

.LBB0_1278:
	v_add_u32_e32 v199, s38, v219
	ds_read_b64_tr_b16 v[194:195], v199 offset:24576
	ds_read_b64_tr_b16 v[196:197], v199 offset:25088
	s_waitcnt lgkmcnt(9)
	v_mfma_f32_32x32x16_bf16 v[114:129], v[98:101], v[170:173], v[50:65]
	v_add_f32_e32 v102, v82, v83
	v_add_f32_e32 v102, v84, v102
	v_add_f32_e32 v102, v85, v102
	v_add_f32_e32 v102, v86, v102
	v_add_f32_e32 v102, v87, v102
	v_cvt_pk_bf16_f32 v174, v82, v83
	v_cvt_pk_bf16_f32 v175, v84, v85
	ds_read_b64_tr_b16 v[190:191], v199 offset:28672
	ds_read_b64_tr_b16 v[192:193], v199 offset:29184
	v_add_f32_e32 v82, v88, v102
	s_waitcnt lgkmcnt(10)
	v_mfma_f32_32x32x16_bf16 v[98:113], v[186:189], v[170:173], v[50:65]
	v_add_f32_e32 v82, v89, v82
	v_add_f32_e32 v82, v90, v82
	v_add_f32_e32 v82, v91, v82
	v_cvt_pk_bf16_f32 v176, v86, v87
	v_cvt_pk_bf16_f32 v177, v88, v89
	ds_read_b64_tr_b16 v[186:187], v199 offset:25600
	ds_read_b64_tr_b16 v[188:189], v199 offset:26112
	s_waitcnt lgkmcnt(11)
	v_mfma_f32_32x32x16_bf16 v[114:129], v[182:185], v[162:165], v[114:129]
	v_add_f32_e32 v82, v92, v82
	v_add_f32_e32 v82, v93, v82
	v_add_f32_e32 v82, v94, v82
	v_add_f32_e32 v82, v95, v82
	v_cvt_pk_bf16_f32 v166, v90, v91
	v_cvt_pk_bf16_f32 v167, v92, v93
	ds_read_b64_tr_b16 v[90:91], v199 offset:29696
	ds_read_b64_tr_b16 v[92:93], v199 offset:30208
	s_waitcnt lgkmcnt(12)
	v_mfma_f32_32x32x16_bf16 v[98:113], v[178:181], v[162:165], v[98:113]
	v_add_f32_e32 v82, v96, v82
	v_add_f32_e32 v82, v97, v82
	v_add_f32_e32 v82, v66, v82
	v_add_f32_e32 v82, v67, v82
	v_cvt_pk_bf16_f32 v168, v94, v95
	v_cvt_pk_bf16_f32 v169, v96, v97
	ds_read_b64_tr_b16 v[86:87], v199 offset:26624
	ds_read_b64_tr_b16 v[88:89], v199 offset:27136
	s_waitcnt lgkmcnt(13)
	v_mfma_f32_32x32x16_bf16 v[114:129], v[142:145], v[154:157], v[114:129]
	v_add_f32_e32 v82, v68, v82
	v_add_f32_e32 v82, v69, v82
	v_add_f32_e32 v82, v70, v82
	v_add_f32_e32 v94, v71, v82
	v_cvt_pk_bf16_f32 v158, v66, v67
	v_cvt_pk_bf16_f32 v159, v68, v69
	ds_read_b64_tr_b16 v[82:83], v199 offset:30720
	ds_read_b64_tr_b16 v[84:85], v199 offset:31232
	s_waitcnt lgkmcnt(14)
	v_mfma_f32_32x32x16_bf16 v[98:113], v[138:141], v[154:157], v[98:113]
	v_add_f32_e32 v66, v72, v94
	v_add_f32_e32 v66, v73, v66
	v_add_f32_e32 v66, v74, v66
	v_add_f32_e32 v66, v75, v66
	v_cvt_pk_bf16_f32 v160, v70, v71
	v_cvt_pk_bf16_f32 v161, v72, v73
	ds_read_b64_tr_b16 v[70:71], v199 offset:27648
	ds_read_b64_tr_b16 v[72:73], v199 offset:28160
	s_waitcnt lgkmcnt(14)
	v_mfma_f32_32x32x16_bf16 v[114:129], v[134:137], v[146:149], v[114:129]
	v_add_f32_e32 v66, v76, v66
	v_add_f32_e32 v66, v77, v66
	v_add_f32_e32 v66, v78, v66
	v_add_f32_e32 v94, v79, v66
	v_cvt_pk_bf16_f32 v150, v74, v75
	v_cvt_pk_bf16_f32 v151, v76, v77
	ds_read_b64_tr_b16 v[66:67], v199 offset:31744
	ds_read_b64_tr_b16 v[68:69], v199 offset:32256
	v_mfma_f32_32x32x16_bf16 v[98:113], v[130:133], v[146:149], v[98:113]
	v_add_f32_e32 v74, v80, v94
	v_add_f32_e32 v76, v81, v74
	v_cvt_pk_bf16_f32 v152, v78, v79
	v_cvt_pk_bf16_f32 v153, v80, v81
	v_lshl_add_u64 v[74:75], v[204:205], 0, s[20:21]
	s_add_i32 s3, s12, s53
	s_mov_b32 s13, m0
	s_mov_b32 m0, s3
	s_nop 0
	global_load_lds_dwordx4 v[74:75], off
	s_mov_b32 m0, s13
	v_lshl_add_u64 v[74:75], v[202:203], 0, s[20:21]
	s_add_i32 s3, s55, s51
	s_mov_b32 s13, m0
	s_mov_b32 m0, s3
	s_nop 0
	global_load_lds_dwordx4 v[74:75], off
	s_mov_b32 m0, s13
	s_nop 0
	s_nop 0
	v_max_f32_e32 v74, v114, v115
	v_max3_f32 v75, v116, v117, v99
	v_max3_f32 v74, v74, v98, v100
	v_max3_f32 v74, v74, v101, v118
	v_max3_f32 v75, v75, v120, v121
	v_max3_f32 v74, v74, v119, v102
	v_max3_f32 v75, v75, v104, v105
	v_max3_f32 v74, v74, v103, v122
	v_max3_f32 v75, v75, v124, v125
	v_max3_f32 v74, v74, v123, v106
	v_max3_f32 v75, v75, v108, v109
	v_max3_f32 v74, v74, v107, v126
	v_max3_f32 v75, v75, v128, v129
	v_max3_f32 v74, v74, v127, v110
	v_max3_f32 v75, v75, v112, v113
	v_max3_f32 v74, v74, v111, v75
	v_mov_b32_e32 v75, v74
	s_nop 1
	v_permlane32_swap_b32_e32 v74, v75
	v_max_f32_e32 v74, v74, v75
	v_cmp_lt_f32_e32 vcc, s48, v74
	s_cmp_lg_u64 vcc, 0
	v_add_f32_e32 v222, v198, v76
	s_cselect_b64 s[38:39], -1, 0
	s_cbranch_vccnz .LBB0_1286

.LBB0_1281:
	s_add_i32 s3, s55, 0x2000
	s_cmpk_lg_i32 s55, 0x4000
	s_cselect_b32 s13, s3, 0
	v_add_u32_e32 v223, s12, v219
	ds_read_b64_tr_b16 v[142:143], v223 offset:24576
	ds_read_b64_tr_b16 v[144:145], v223 offset:25088
	s_waitcnt lgkmcnt(9)
	v_mfma_f32_32x32x16_bf16 v[82:97], v[74:77], v[170:173], v[50:65]
	v_add_f32_e32 v66, v114, v115
	v_add_f32_e32 v66, v116, v66
	v_add_f32_e32 v66, v117, v66
	v_add_f32_e32 v66, v118, v66
	v_add_f32_e32 v66, v119, v66
	v_cvt_pk_bf16_f32 v174, v114, v115
	v_cvt_pk_bf16_f32 v175, v116, v117
	ds_read_b64_tr_b16 v[138:139], v223 offset:28672
	ds_read_b64_tr_b16 v[140:141], v223 offset:29184
	v_add_f32_e32 v66, v120, v66
	v_add_f32_e32 v66, v121, v66
	v_add_f32_e32 v66, v122, v66
	v_add_f32_e32 v114, v123, v66
	s_waitcnt lgkmcnt(10)
	v_mfma_f32_32x32x16_bf16 v[66:81], v[130:133], v[170:173], v[50:65]
	v_cvt_pk_bf16_f32 v176, v118, v119
	v_cvt_pk_bf16_f32 v177, v120, v121
	ds_read_b64_tr_b16 v[134:135], v223 offset:25600
	ds_read_b64_tr_b16 v[136:137], v223 offset:26112
	s_waitcnt lgkmcnt(11)
	v_mfma_f32_32x32x16_bf16 v[82:97], v[198:201], v[162:165], v[82:97]
	v_add_f32_e32 v114, v124, v114
	v_add_f32_e32 v114, v125, v114
	v_add_f32_e32 v114, v126, v114
	v_add_f32_e32 v114, v127, v114
	v_cvt_pk_bf16_f32 v166, v122, v123
	v_cvt_pk_bf16_f32 v167, v124, v125
	ds_read_b64_tr_b16 v[130:131], v223 offset:29696
	ds_read_b64_tr_b16 v[132:133], v223 offset:30208
	s_waitcnt lgkmcnt(12)
	v_mfma_f32_32x32x16_bf16 v[66:81], v[190:193], v[162:165], v[66:81]
	v_add_f32_e32 v114, v128, v114
	v_add_f32_e32 v114, v129, v114
	v_add_f32_e32 v114, v98, v114
	v_add_f32_e32 v114, v99, v114
	v_cvt_pk_bf16_f32 v168, v126, v127
	v_cvt_pk_bf16_f32 v169, v128, v129
	ds_read_b64_tr_b16 v[122:123], v223 offset:26624
	ds_read_b64_tr_b16 v[124:125], v223 offset:27136
	s_waitcnt lgkmcnt(13)
	v_mfma_f32_32x32x16_bf16 v[82:97], v[194:197], v[154:157], v[82:97]
	v_add_f32_e32 v114, v100, v114
	v_add_f32_e32 v114, v101, v114
	v_add_f32_e32 v114, v102, v114
	v_add_f32_e32 v114, v103, v114
	v_cvt_pk_bf16_f32 v158, v98, v99
	v_cvt_pk_bf16_f32 v159, v100, v101
	ds_read_b64_tr_b16 v[118:119], v223 offset:30720
	ds_read_b64_tr_b16 v[120:121], v223 offset:31232
	s_waitcnt lgkmcnt(14)
	v_mfma_f32_32x32x16_bf16 v[66:81], v[182:185], v[154:157], v[66:81]
	v_add_f32_e32 v98, v104, v114
	v_add_f32_e32 v98, v105, v98
	v_add_f32_e32 v98, v106, v98
	v_add_f32_e32 v98, v107, v98
	v_cvt_pk_bf16_f32 v160, v102, v103
	v_cvt_pk_bf16_f32 v161, v104, v105
	ds_read_b64_tr_b16 v[114:115], v223 offset:27648
	ds_read_b64_tr_b16 v[116:117], v223 offset:28160
	s_waitcnt lgkmcnt(14)
	v_mfma_f32_32x32x16_bf16 v[82:97], v[186:189], v[146:149], v[82:97]
	v_add_f32_e32 v98, v108, v98
	v_add_f32_e32 v98, v109, v98
	v_add_f32_e32 v98, v110, v98
	v_add_f32_e32 v98, v111, v98
	v_cvt_pk_bf16_f32 v150, v106, v107
	v_cvt_pk_bf16_f32 v151, v108, v109
	ds_read_b64_tr_b16 v[102:103], v223 offset:31744
	ds_read_b64_tr_b16 v[104:105], v223 offset:32256
	v_mfma_f32_32x32x16_bf16 v[66:81], v[178:181], v[146:149], v[66:81]
	v_add_f32_e32 v98, v112, v98
	v_add_f32_e32 v98, v113, v98
	v_cvt_pk_bf16_f32 v152, v110, v111
	v_cvt_pk_bf16_f32 v153, v112, v113
	s_nop 0
	s_nop 0
	v_max_f32_e32 v99, v82, v83
	s_nop 3
	v_max3_f32 v100, v84, v85, v67
	v_max3_f32 v99, v99, v66, v68
	v_max3_f32 v99, v99, v69, v86
	v_max3_f32 v100, v100, v88, v89
	v_max3_f32 v99, v99, v87, v70
	v_max3_f32 v100, v100, v72, v73
	v_max3_f32 v99, v99, v71, v90
	v_max3_f32 v100, v100, v92, v93
	v_max3_f32 v99, v99, v91, v74
	v_max3_f32 v100, v100, v76, v77
	v_max3_f32 v99, v99, v75, v94
	v_max3_f32 v100, v100, v96, v97
	v_max3_f32 v99, v99, v95, v78
	v_max3_f32 v100, v100, v80, v81
	v_add_f32_e32 v198, v222, v98
	v_max3_f32 v98, v99, v79, v100
	v_mov_b32_e32 v99, v98
	s_nop 1
	v_permlane32_swap_b32_e32 v98, v99
	s_add_i32 s3, s55, s53
	s_mov_b32 s12, m0
	s_mov_b32 m0, s3
	s_nop 0
	global_load_lds_dwordx4 v[204:205], off
	s_mov_b32 m0, s12
	v_max_f32_e32 v98, v98, v99
	s_add_i32 s3, s13, s51
	s_mov_b32 s12, m0
	s_mov_b32 m0, s3
	s_nop 0
	global_load_lds_dwordx4 v[202:203], off
	s_mov_b32 m0, s12
	v_cmp_lt_f32_e32 vcc, s48, v98
	s_cmp_lg_u64 vcc, 0
	s_cselect_b64 s[38:39], -1, 0
	s_cbranch_vccnz .LBB0_1289

.LBB0_1292:
	ds_read_b64_tr_b16 v[194:195], v219 offset:24576
	ds_read_b64_tr_b16 v[196:197], v219 offset:25088
	s_waitcnt lgkmcnt(9)
	v_mfma_f32_32x32x16_bf16 v[114:129], v[98:101], v[170:173], v[50:65]
	v_add_f32_e32 v102, v82, v83
	v_add_f32_e32 v102, v84, v102
	v_add_f32_e32 v102, v85, v102
	v_add_f32_e32 v102, v86, v102
	v_add_f32_e32 v102, v87, v102
	v_cvt_pk_bf16_f32 v174, v82, v83
	v_cvt_pk_bf16_f32 v175, v84, v85
	ds_read_b64_tr_b16 v[190:191], v219 offset:28672
	ds_read_b64_tr_b16 v[192:193], v219 offset:29184
	v_add_f32_e32 v82, v88, v102
	s_waitcnt lgkmcnt(10)
	v_mfma_f32_32x32x16_bf16 v[98:113], v[186:189], v[170:173], v[50:65]
	v_add_f32_e32 v82, v89, v82
	v_add_f32_e32 v82, v90, v82
	v_add_f32_e32 v82, v91, v82
	v_cvt_pk_bf16_f32 v176, v86, v87
	v_cvt_pk_bf16_f32 v177, v88, v89
	ds_read_b64_tr_b16 v[186:187], v219 offset:25600
	ds_read_b64_tr_b16 v[188:189], v219 offset:26112
	s_waitcnt lgkmcnt(11)
	v_mfma_f32_32x32x16_bf16 v[114:129], v[182:185], v[162:165], v[114:129]
	v_add_f32_e32 v82, v92, v82
	v_add_f32_e32 v82, v93, v82
	v_add_f32_e32 v82, v94, v82
	v_add_f32_e32 v82, v95, v82
	v_cvt_pk_bf16_f32 v166, v90, v91
	v_cvt_pk_bf16_f32 v167, v92, v93
	ds_read_b64_tr_b16 v[90:91], v219 offset:29696
	ds_read_b64_tr_b16 v[92:93], v219 offset:30208
	s_waitcnt lgkmcnt(12)
	v_mfma_f32_32x32x16_bf16 v[98:113], v[178:181], v[162:165], v[98:113]
	v_add_f32_e32 v82, v96, v82
	v_add_f32_e32 v82, v97, v82
	v_add_f32_e32 v82, v66, v82
	v_add_f32_e32 v82, v67, v82
	v_cvt_pk_bf16_f32 v168, v94, v95
	v_cvt_pk_bf16_f32 v169, v96, v97
	ds_read_b64_tr_b16 v[86:87], v219 offset:26624
	ds_read_b64_tr_b16 v[88:89], v219 offset:27136
	s_waitcnt lgkmcnt(13)
	v_mfma_f32_32x32x16_bf16 v[114:129], v[142:145], v[154:157], v[114:129]
	v_add_f32_e32 v82, v68, v82
	v_add_f32_e32 v82, v69, v82
	v_add_f32_e32 v82, v70, v82
	v_add_f32_e32 v94, v71, v82
	v_cvt_pk_bf16_f32 v158, v66, v67
	v_cvt_pk_bf16_f32 v159, v68, v69
	ds_read_b64_tr_b16 v[82:83], v219 offset:30720
	ds_read_b64_tr_b16 v[84:85], v219 offset:31232
	s_waitcnt lgkmcnt(14)
	v_mfma_f32_32x32x16_bf16 v[98:113], v[138:141], v[154:157], v[98:113]
	v_add_f32_e32 v66, v72, v94
	v_add_f32_e32 v66, v73, v66
	v_add_f32_e32 v66, v74, v66
	v_add_f32_e32 v66, v75, v66
	v_cvt_pk_bf16_f32 v160, v70, v71
	v_cvt_pk_bf16_f32 v161, v72, v73
	ds_read_b64_tr_b16 v[70:71], v219 offset:27648
	ds_read_b64_tr_b16 v[72:73], v219 offset:28160
	s_waitcnt lgkmcnt(14)
	v_mfma_f32_32x32x16_bf16 v[114:129], v[134:137], v[146:149], v[114:129]
	v_add_f32_e32 v66, v76, v66
	v_add_f32_e32 v66, v77, v66
	v_add_f32_e32 v66, v78, v66
	v_add_f32_e32 v94, v79, v66
	v_cvt_pk_bf16_f32 v150, v74, v75
	v_cvt_pk_bf16_f32 v151, v76, v77
	ds_read_b64_tr_b16 v[66:67], v219 offset:31744
	ds_read_b64_tr_b16 v[68:69], v219 offset:32256
	v_mfma_f32_32x32x16_bf16 v[98:113], v[130:133], v[146:149], v[98:113]
	v_add_f32_e32 v74, v80, v94
	v_add_f32_e32 v74, v81, v74
	v_cvt_pk_bf16_f32 v152, v78, v79
	v_cvt_pk_bf16_f32 v153, v80, v81
	s_cmp_lg_u32 0, -1
	s_cselect_b32 s3, 0, 0
	v_add_f32_e32 v222, v198, v74
	v_lshl_add_u64 v[74:75], v[210:211], 0, s[22:23]
	s_add_i32 s53, s3, s50
	s_add_i32 s3, s53, 0x2000
	s_mov_b32 s12, m0
	s_mov_b32 m0, s3
	s_nop 0
	global_load_lds_dwordx4 v[74:75], off
	s_mov_b32 m0, s12
	v_lshl_add_u64 v[74:75], v[208:209], 0, s[24:25]
	s_add_i32 s53, s53, 0xa000
	s_mov_b32 s3, m0
	s_mov_b32 m0, s53
	s_nop 0
	global_load_lds_dwordx4 v[74:75], off
	s_mov_b32 m0, s3
	s_nop 0
	s_nop 0
	v_max_f32_e32 v74, v114, v115
	v_max3_f32 v75, v116, v117, v99
	v_max3_f32 v74, v74, v98, v100
	v_max3_f32 v74, v74, v101, v118
	v_max3_f32 v75, v75, v120, v121
	v_max3_f32 v74, v74, v119, v102
	v_max3_f32 v75, v75, v104, v105
	v_max3_f32 v74, v74, v103, v122
	v_max3_f32 v75, v75, v124, v125
	v_max3_f32 v74, v74, v123, v106
	v_max3_f32 v75, v75, v108, v109
	v_max3_f32 v74, v74, v107, v126
	v_max3_f32 v75, v75, v128, v129
	v_max3_f32 v74, v74, v127, v110
	v_max3_f32 v75, v75, v112, v113
	v_max3_f32 v74, v74, v111, v75
	v_mov_b32_e32 v75, v74
	s_nop 1
	v_permlane32_swap_b32_e32 v74, v75
	v_max_f32_e32 v74, v74, v75
	v_cmp_lt_f32_e32 vcc, s48, v74
	s_cmp_lg_u64 vcc, 0
	s_cselect_b64 s[38:39], -1, 0
	s_cbranch_vccnz .LBB0_1309

.LBB0_1295:
	ds_read_b64_tr_b16 v[182:183], v219 offset:32768
	ds_read_b64_tr_b16 v[184:185], v219 offset:33280
	s_waitcnt lgkmcnt(9)
	v_mfma_f32_32x32x16_bf16 v[130:145], v[74:77], v[170:173], v[50:65]
	v_add_f32_e32 v66, v114, v115
	v_add_f32_e32 v66, v116, v66
	v_add_f32_e32 v66, v117, v66
	v_add_f32_e32 v66, v118, v66
	v_add_f32_e32 v66, v119, v66
	v_cvt_pk_bf16_f32 v174, v114, v115
	v_cvt_pk_bf16_f32 v175, v116, v117
	ds_read_b64_tr_b16 v[178:179], v219 offset:36864
	ds_read_b64_tr_b16 v[180:181], v219 offset:37376
	v_add_f32_e32 v66, v120, v66
	v_add_f32_e32 v66, v121, v66
	v_add_f32_e32 v66, v122, v66
	v_add_f32_e32 v82, v123, v66
	s_waitcnt lgkmcnt(10)
	v_mfma_f32_32x32x16_bf16 v[66:81], v[198:201], v[170:173], v[50:65]
	v_cvt_pk_bf16_f32 v176, v118, v119
	v_cvt_pk_bf16_f32 v177, v120, v121
	ds_read_b64_tr_b16 v[118:119], v219 offset:33792
	ds_read_b64_tr_b16 v[120:121], v219 offset:34304
	s_waitcnt lgkmcnt(11)
	v_mfma_f32_32x32x16_bf16 v[130:145], v[202:205], v[162:165], v[130:145]
	v_add_f32_e32 v82, v124, v82
	v_add_f32_e32 v82, v125, v82
	v_add_f32_e32 v82, v126, v82
	v_add_f32_e32 v82, v127, v82
	v_cvt_pk_bf16_f32 v166, v122, v123
	v_cvt_pk_bf16_f32 v167, v124, v125
	ds_read_b64_tr_b16 v[114:115], v219 offset:37888
	ds_read_b64_tr_b16 v[116:117], v219 offset:38400
	s_waitcnt lgkmcnt(12)
	v_mfma_f32_32x32x16_bf16 v[66:81], v[94:97], v[162:165], v[66:81]
	v_add_f32_e32 v82, v128, v82
	v_add_f32_e32 v82, v129, v82
	v_add_f32_e32 v82, v98, v82
	v_add_f32_e32 v82, v99, v82
	v_cvt_pk_bf16_f32 v168, v126, v127
	v_cvt_pk_bf16_f32 v169, v128, v129
	ds_read_b64_tr_b16 v[94:95], v219 offset:34816
	ds_read_b64_tr_b16 v[96:97], v219 offset:35328
	s_waitcnt lgkmcnt(13)
	v_mfma_f32_32x32x16_bf16 v[130:145], v[90:93], v[154:157], v[130:145]
	v_add_f32_e32 v82, v100, v82
	v_add_f32_e32 v82, v101, v82
	v_add_f32_e32 v82, v102, v82
	v_add_f32_e32 v82, v103, v82
	v_cvt_pk_bf16_f32 v158, v98, v99
	v_cvt_pk_bf16_f32 v159, v100, v101
	ds_read_b64_tr_b16 v[90:91], v219 offset:38912
	ds_read_b64_tr_b16 v[92:93], v219 offset:39424
	s_waitcnt lgkmcnt(14)
	v_mfma_f32_32x32x16_bf16 v[66:81], v[190:193], v[154:157], v[66:81]
	v_add_f32_e32 v82, v104, v82
	v_add_f32_e32 v82, v105, v82
	v_add_f32_e32 v82, v106, v82
	v_add_f32_e32 v82, v107, v82
	v_cvt_pk_bf16_f32 v160, v102, v103
	v_cvt_pk_bf16_f32 v161, v104, v105
	ds_read_b64_tr_b16 v[86:87], v219 offset:35840
	ds_read_b64_tr_b16 v[88:89], v219 offset:36352
	s_waitcnt lgkmcnt(14)
	v_mfma_f32_32x32x16_bf16 v[130:145], v[194:197], v[146:149], v[130:145]
	v_add_f32_e32 v82, v108, v82
	v_add_f32_e32 v82, v109, v82
	v_add_f32_e32 v82, v110, v82
	v_add_f32_e32 v98, v111, v82
	v_cvt_pk_bf16_f32 v150, v106, v107
	v_cvt_pk_bf16_f32 v151, v108, v109
	ds_read_b64_tr_b16 v[82:83], v219 offset:39936
	ds_read_b64_tr_b16 v[84:85], v219 offset:40448
	v_mfma_f32_32x32x16_bf16 v[66:81], v[186:189], v[146:149], v[66:81]
	v_add_f32_e32 v98, v112, v98
	v_add_f32_e32 v98, v113, v98
	v_cvt_pk_bf16_f32 v152, v110, v111
	v_cvt_pk_bf16_f32 v153, v112, v113
	s_cmp_lg_u32 0, -1
	s_cselect_b32 s3, 0, 0
	v_add_f32_e32 v198, v222, v98
	v_lshl_add_u64 v[98:99], v[210:211], 0, s[26:27]
	s_add_i32 s3, s3, s50
	s_addk_i32 s3, 0x4000
	s_mov_b32 s12, m0
	s_mov_b32 m0, s3
	s_nop 0
	global_load_lds_dwordx4 v[98:99], off
	s_mov_b32 m0, s12
	v_lshl_add_u64 v[98:99], v[208:209], 0, s[28:29]
	s_mov_b32 s3, m0
	s_mov_b32 m0, s51
	s_nop 0
	global_load_lds_dwordx4 v[98:99], off
	s_mov_b32 m0, s3
	s_nop 0
	s_nop 0
	v_max_f32_e32 v98, v130, v131
	v_max3_f32 v99, v132, v133, v67
	v_max3_f32 v98, v98, v66, v68
	v_max3_f32 v98, v98, v69, v134
	v_max3_f32 v99, v99, v136, v137
	v_max3_f32 v98, v98, v135, v70
	v_max3_f32 v99, v99, v72, v73
	v_max3_f32 v98, v98, v71, v138
	v_max3_f32 v99, v99, v140, v141
	v_max3_f32 v98, v98, v139, v74
	v_max3_f32 v99, v99, v76, v77
	v_max3_f32 v98, v98, v75, v142
	v_max3_f32 v99, v99, v144, v145
	v_max3_f32 v98, v98, v143, v78
	v_max3_f32 v99, v99, v80, v81
	v_max3_f32 v98, v98, v79, v99
	v_mov_b32_e32 v99, v98
	s_nop 1
	v_permlane32_swap_b32_e32 v98, v99
	v_max_f32_e32 v98, v98, v99
	v_cmp_lt_f32_e32 vcc, s48, v98
	s_cmp_lg_u64 vcc, 0
	s_cselect_b64 s[38:39], -1, 0
	s_cbranch_vccnz .LBB0_1312

.LBB0_1298:
	ds_read_b64_tr_b16 v[178:179], v219 offset:40960
	ds_read_b64_tr_b16 v[180:181], v219 offset:41472
	s_waitcnt lgkmcnt(9)
	v_mfma_f32_32x32x16_bf16 v[98:113], v[126:129], v[170:173], v[50:65]
	v_add_f32_e32 v82, v130, v131
	v_add_f32_e32 v82, v132, v82
	v_add_f32_e32 v82, v133, v82
	v_add_f32_e32 v82, v134, v82
	v_add_f32_e32 v82, v135, v82
	v_cvt_pk_bf16_f32 v174, v130, v131
	v_cvt_pk_bf16_f32 v175, v132, v133
	ds_read_b64_tr_b16 v[130:131], v219 offset:45056
	ds_read_b64_tr_b16 v[132:133], v219 offset:45568
	v_add_f32_e32 v82, v136, v82
	v_add_f32_e32 v82, v137, v82
	v_add_f32_e32 v82, v138, v82
	v_add_f32_e32 v150, v139, v82
	s_waitcnt lgkmcnt(10)
	v_mfma_f32_32x32x16_bf16 v[82:97], v[122:125], v[170:173], v[50:65]
	v_cvt_pk_bf16_f32 v176, v134, v135
	v_cvt_pk_bf16_f32 v177, v136, v137
	ds_read_b64_tr_b16 v[126:127], v219 offset:41984
	ds_read_b64_tr_b16 v[128:129], v219 offset:42496
	s_waitcnt lgkmcnt(11)
	v_mfma_f32_32x32x16_bf16 v[98:113], v[194:197], v[162:165], v[98:113]
	v_add_f32_e32 v122, v140, v150
	v_add_f32_e32 v122, v141, v122
	v_add_f32_e32 v122, v142, v122
	v_add_f32_e32 v134, v143, v122
	v_cvt_pk_bf16_f32 v166, v138, v139
	v_cvt_pk_bf16_f32 v167, v140, v141
	ds_read_b64_tr_b16 v[122:123], v219 offset:46080
	ds_read_b64_tr_b16 v[124:125], v219 offset:46592
	s_waitcnt lgkmcnt(12)
	v_mfma_f32_32x32x16_bf16 v[82:97], v[118:121], v[162:165], v[82:97]
	v_add_f32_e32 v134, v144, v134
	v_add_f32_e32 v134, v145, v134
	v_add_f32_e32 v134, v66, v134
	v_add_f32_e32 v134, v67, v134
	v_cvt_pk_bf16_f32 v168, v142, v143
	v_cvt_pk_bf16_f32 v169, v144, v145
	ds_read_b64_tr_b16 v[118:119], v219 offset:43008
	ds_read_b64_tr_b16 v[120:121], v219 offset:43520
	s_waitcnt lgkmcnt(13)
	v_mfma_f32_32x32x16_bf16 v[98:113], v[114:117], v[154:157], v[98:113]
	v_add_f32_e32 v134, v68, v134
	v_add_f32_e32 v134, v69, v134
	v_add_f32_e32 v134, v70, v134
	v_add_f32_e32 v134, v71, v134
	v_cvt_pk_bf16_f32 v158, v66, v67
	v_cvt_pk_bf16_f32 v159, v68, v69
	ds_read_b64_tr_b16 v[114:115], v219 offset:47104
	ds_read_b64_tr_b16 v[116:117], v219 offset:47616
	s_waitcnt lgkmcnt(14)
	v_mfma_f32_32x32x16_bf16 v[82:97], v[186:189], v[154:157], v[82:97]
	v_add_f32_e32 v66, v72, v134
	v_add_f32_e32 v66, v73, v66
	v_add_f32_e32 v66, v74, v66
	v_add_f32_e32 v66, v75, v66
	v_cvt_pk_bf16_f32 v160, v70, v71
	v_cvt_pk_bf16_f32 v161, v72, v73
	ds_read_b64_tr_b16 v[70:71], v219 offset:44032
	ds_read_b64_tr_b16 v[72:73], v219 offset:44544
	s_waitcnt lgkmcnt(14)
	v_mfma_f32_32x32x16_bf16 v[98:113], v[190:193], v[146:149], v[98:113]
	v_add_f32_e32 v66, v76, v66
	v_add_f32_e32 v66, v77, v66
	v_add_f32_e32 v66, v78, v66
	v_add_f32_e32 v134, v79, v66
	v_cvt_pk_bf16_f32 v150, v74, v75
	v_cvt_pk_bf16_f32 v151, v76, v77
	ds_read_b64_tr_b16 v[66:67], v219 offset:48128
	ds_read_b64_tr_b16 v[68:69], v219 offset:48640
	v_mfma_f32_32x32x16_bf16 v[82:97], v[182:185], v[146:149], v[82:97]
	v_add_f32_e32 v74, v80, v134
	v_add_f32_e32 v74, v81, v74
	v_cvt_pk_bf16_f32 v152, v78, v79
	v_cvt_pk_bf16_f32 v153, v80, v81
	s_cmp_lg_u32 0, -1
	s_cselect_b32 s3, 0, 0
	v_add_f32_e32 v198, v198, v74
	v_lshl_add_u64 v[74:75], v[208:209], 0, s[22:23]
	s_add_i32 s3, s3, s50
	s_add_i32 s3, s3, 0x8000
	s_mov_b32 s12, m0
	s_mov_b32 m0, s3
	s_nop 0
	global_load_lds_dwordx4 v[74:75], off
	s_mov_b32 m0, s12
	s_nop 0
	s_nop 0
	v_max_f32_e32 v74, v98, v99
	v_max3_f32 v75, v100, v101, v83
	v_max3_f32 v74, v74, v82, v84
	v_max3_f32 v74, v74, v85, v102
	v_max3_f32 v75, v75, v104, v105
	v_max3_f32 v74, v74, v103, v86
	v_max3_f32 v75, v75, v88, v89
	v_max3_f32 v74, v74, v87, v106
	v_max3_f32 v75, v75, v108, v109
	v_max3_f32 v74, v74, v107, v90
	v_max3_f32 v75, v75, v92, v93
	v_max3_f32 v74, v74, v91, v110
	v_max3_f32 v75, v75, v112, v113
	v_max3_f32 v74, v74, v111, v94
	v_max3_f32 v75, v75, v96, v97
	v_max3_f32 v74, v74, v95, v75
	v_mov_b32_e32 v75, v74
	s_nop 1
	v_permlane32_swap_b32_e32 v74, v75
	v_max_f32_e32 v74, v74, v75
	v_cmp_lt_f32_e32 vcc, s48, v74
	s_cmp_lg_u64 vcc, 0
	s_cselect_b64 s[38:39], -1, 0
	s_cbranch_vccnz .LBB0_1315

.LBB0_1301:
	ds_read_b64_tr_b16 v[138:139], v219 offset:24576
	ds_read_b64_tr_b16 v[140:141], v219 offset:25088
	s_waitcnt lgkmcnt(9)
	v_mfma_f32_32x32x16_bf16 v[114:129], v[74:77], v[170:173], v[50:65]
	v_add_f32_e32 v66, v98, v99
	v_add_f32_e32 v66, v100, v66
	v_add_f32_e32 v66, v101, v66
	v_add_f32_e32 v66, v102, v66
	v_add_f32_e32 v66, v103, v66
	v_cvt_pk_bf16_f32 v174, v98, v99
	v_cvt_pk_bf16_f32 v175, v100, v101
	ds_read_b64_tr_b16 v[134:135], v219 offset:28672
	ds_read_b64_tr_b16 v[136:137], v219 offset:29184
	v_add_f32_e32 v66, v104, v66
	v_add_f32_e32 v66, v105, v66
	v_add_f32_e32 v66, v106, v66
	v_add_f32_e32 v98, v107, v66
	s_waitcnt lgkmcnt(10)
	v_mfma_f32_32x32x16_bf16 v[66:81], v[130:133], v[170:173], v[50:65]
	v_cvt_pk_bf16_f32 v176, v102, v103
	v_cvt_pk_bf16_f32 v177, v104, v105
	ds_read_b64_tr_b16 v[130:131], v219 offset:25600
	ds_read_b64_tr_b16 v[132:133], v219 offset:26112
	s_waitcnt lgkmcnt(11)
	v_mfma_f32_32x32x16_bf16 v[114:129], v[194:197], v[162:165], v[114:129]
	v_add_f32_e32 v98, v108, v98
	v_add_f32_e32 v98, v109, v98
	v_add_f32_e32 v98, v110, v98
	v_add_f32_e32 v98, v111, v98
	v_cvt_pk_bf16_f32 v166, v106, v107
	v_cvt_pk_bf16_f32 v167, v108, v109
	ds_read_b64_tr_b16 v[106:107], v219 offset:29696
	ds_read_b64_tr_b16 v[108:109], v219 offset:30208
	s_waitcnt lgkmcnt(12)
	v_mfma_f32_32x32x16_bf16 v[66:81], v[186:189], v[162:165], v[66:81]
	v_add_f32_e32 v98, v112, v98
	v_add_f32_e32 v98, v113, v98
	v_add_f32_e32 v98, v82, v98
	v_add_f32_e32 v98, v83, v98
	v_cvt_pk_bf16_f32 v168, v110, v111
	v_cvt_pk_bf16_f32 v169, v112, v113
	ds_read_b64_tr_b16 v[102:103], v219 offset:26624
	ds_read_b64_tr_b16 v[104:105], v219 offset:27136
	s_waitcnt lgkmcnt(13)
	v_mfma_f32_32x32x16_bf16 v[114:129], v[190:193], v[154:157], v[114:129]
	v_add_f32_e32 v98, v84, v98
	v_add_f32_e32 v98, v85, v98
	v_add_f32_e32 v98, v86, v98
	v_add_f32_e32 v110, v87, v98
	v_cvt_pk_bf16_f32 v158, v82, v83
	v_cvt_pk_bf16_f32 v159, v84, v85
	ds_read_b64_tr_b16 v[98:99], v219 offset:30720
	ds_read_b64_tr_b16 v[100:101], v219 offset:31232
	s_waitcnt lgkmcnt(14)
	v_mfma_f32_32x32x16_bf16 v[66:81], v[178:181], v[154:157], v[66:81]
	v_add_f32_e32 v82, v88, v110
	v_add_f32_e32 v82, v89, v82
	v_add_f32_e32 v82, v90, v82
	v_add_f32_e32 v82, v91, v82
	v_cvt_pk_bf16_f32 v160, v86, v87
	v_cvt_pk_bf16_f32 v161, v88, v89
	ds_read_b64_tr_b16 v[86:87], v219 offset:27648
	ds_read_b64_tr_b16 v[88:89], v219 offset:28160
	s_waitcnt lgkmcnt(14)
	v_mfma_f32_32x32x16_bf16 v[114:129], v[182:185], v[146:149], v[114:129]
	v_add_f32_e32 v82, v92, v82
	v_add_f32_e32 v82, v93, v82
	v_add_f32_e32 v82, v94, v82
	v_add_f32_e32 v110, v95, v82
	v_cvt_pk_bf16_f32 v150, v90, v91
	v_cvt_pk_bf16_f32 v151, v92, v93
	ds_read_b64_tr_b16 v[82:83], v219 offset:31744
	ds_read_b64_tr_b16 v[84:85], v219 offset:32256
	v_mfma_f32_32x32x16_bf16 v[66:81], v[142:145], v[146:149], v[66:81]
	v_add_f32_e32 v90, v96, v110
	v_add_f32_e32 v90, v97, v90
	v_cvt_pk_bf16_f32 v152, v94, v95
	v_cvt_pk_bf16_f32 v153, v96, v97
	s_nop 0
	v_add_f32_e32 v190, v198, v90
	v_lshl_add_u64 v[90:91], v[208:209], 0, s[26:27]
	s_mov_b32 s3, m0
	s_mov_b32 m0, s53
	s_nop 0
	global_load_lds_dwordx4 v[90:91], off
	s_mov_b32 m0, s3
	s_nop 0
	s_nop 0
	v_max_f32_e32 v90, v114, v115
	s_nop 0
	v_max3_f32 v91, v116, v117, v67
	v_max3_f32 v90, v90, v66, v68
	v_max3_f32 v90, v90, v69, v118
	v_max3_f32 v91, v91, v120, v121
	v_max3_f32 v90, v90, v119, v70
	v_max3_f32 v91, v91, v72, v73
	v_max3_f32 v90, v90, v71, v122
	v_max3_f32 v91, v91, v124, v125
	v_max3_f32 v90, v90, v123, v74
	v_max3_f32 v91, v91, v76, v77
	v_max3_f32 v90, v90, v75, v126
	v_max3_f32 v91, v91, v128, v129
	v_max3_f32 v90, v90, v127, v78
	v_max3_f32 v91, v91, v80, v81
	v_max3_f32 v90, v90, v79, v91
	v_mov_b32_e32 v91, v90
	s_nop 1
	v_permlane32_swap_b32_e32 v90, v91
	v_max_f32_e32 v90, v90, v91
	v_cmp_lt_f32_e32 vcc, s48, v90
	s_cmp_lg_u64 vcc, 0
	s_cselect_b64 s[38:39], -1, 0
	s_cbranch_vccnz .LBB0_1318

.LBB0_1304:
	ds_read_b64_tr_b16 v[138:139], v219 offset:32768
	ds_read_b64_tr_b16 v[140:141], v219 offset:33280
	v_add_f32_e32 v82, v114, v115
	v_add_f32_e32 v82, v116, v82
	v_add_f32_e32 v82, v117, v82
	v_add_f32_e32 v82, v118, v82
	v_add_f32_e32 v98, v119, v82
	s_waitcnt lgkmcnt(9)
	v_mfma_f32_32x32x16_bf16 v[82:97], v[134:137], v[170:173], v[50:65]
	v_cvt_pk_bf16_f32 v174, v114, v115
	v_cvt_pk_bf16_f32 v175, v116, v117
	ds_read_b64_tr_b16 v[134:135], v219 offset:36864
	ds_read_b64_tr_b16 v[136:137], v219 offset:37376
	s_waitcnt lgkmcnt(10)
	v_mfma_f32_32x32x16_bf16 v[50:65], v[182:185], v[170:173], v[50:65]
	v_add_f32_e32 v98, v120, v98
	v_add_f32_e32 v98, v121, v98
	v_add_f32_e32 v98, v122, v98
	v_add_f32_e32 v98, v123, v98
	v_cvt_pk_bf16_f32 v176, v118, v119
	v_cvt_pk_bf16_f32 v177, v120, v121
	ds_read_b64_tr_b16 v[130:131], v219 offset:33792
	ds_read_b64_tr_b16 v[132:133], v219 offset:34304
	s_waitcnt lgkmcnt(11)
	v_mfma_f32_32x32x16_bf16 v[82:97], v[186:189], v[162:165], v[82:97]
	v_add_f32_e32 v98, v124, v98
	v_add_f32_e32 v98, v125, v98
	v_add_f32_e32 v98, v126, v98
	v_add_f32_e32 v98, v127, v98
	v_cvt_pk_bf16_f32 v166, v122, v123
	v_cvt_pk_bf16_f32 v167, v124, v125
	ds_read_b64_tr_b16 v[118:119], v219 offset:37888
	ds_read_b64_tr_b16 v[120:121], v219 offset:38400
	s_waitcnt lgkmcnt(12)
	v_mfma_f32_32x32x16_bf16 v[50:65], v[110:113], v[162:165], v[50:65]
	v_add_f32_e32 v98, v128, v98
	v_add_f32_e32 v98, v129, v98
	v_add_f32_e32 v98, v66, v98
	v_add_f32_e32 v98, v67, v98
	v_cvt_pk_bf16_f32 v168, v126, v127
	v_cvt_pk_bf16_f32 v169, v128, v129
	ds_read_b64_tr_b16 v[114:115], v219 offset:34816
	ds_read_b64_tr_b16 v[116:117], v219 offset:35328
	s_waitcnt lgkmcnt(13)
	v_mfma_f32_32x32x16_bf16 v[82:97], v[178:181], v[154:157], v[82:97]
	v_add_f32_e32 v98, v68, v98
	v_add_f32_e32 v98, v69, v98
	v_add_f32_e32 v98, v70, v98
	v_add_f32_e32 v98, v71, v98
	v_cvt_pk_bf16_f32 v158, v66, v67
	v_cvt_pk_bf16_f32 v159, v68, v69
	ds_read_b64_tr_b16 v[110:111], v219 offset:38912
	ds_read_b64_tr_b16 v[112:113], v219 offset:39424
	s_waitcnt lgkmcnt(14)
	v_mfma_f32_32x32x16_bf16 v[50:65], v[106:109], v[154:157], v[50:65]
	v_add_f32_e32 v66, v72, v98
	v_add_f32_e32 v66, v73, v66
	v_add_f32_e32 v66, v74, v66
	v_add_f32_e32 v66, v75, v66
	v_cvt_pk_bf16_f32 v160, v70, v71
	v_cvt_pk_bf16_f32 v161, v72, v73
	ds_read_b64_tr_b16 v[106:107], v219 offset:35840
	ds_read_b64_tr_b16 v[108:109], v219 offset:36352
	s_waitcnt lgkmcnt(14)
	v_mfma_f32_32x32x16_bf16 v[82:97], v[142:145], v[146:149], v[82:97]
	v_add_f32_e32 v66, v76, v66
	v_add_f32_e32 v66, v77, v66
	v_add_f32_e32 v66, v78, v66
	v_add_f32_e32 v66, v79, v66
	v_cvt_pk_bf16_f32 v150, v74, v75
	v_cvt_pk_bf16_f32 v151, v76, v77
	ds_read_b64_tr_b16 v[98:99], v219 offset:39936
	ds_read_b64_tr_b16 v[100:101], v219 offset:40448
	v_mfma_f32_32x32x16_bf16 v[50:65], v[102:105], v[146:149], v[50:65]
	v_add_f32_e32 v66, v80, v66
	v_add_f32_e32 v66, v81, v66
	v_cvt_pk_bf16_f32 v152, v78, v79
	v_cvt_pk_bf16_f32 v153, v80, v81
	s_nop 0
	s_nop 0
	v_max_f32_e32 v67, v82, v83
	s_nop 3
	v_max3_f32 v68, v84, v85, v51
	v_max3_f32 v67, v67, v50, v52
	v_max3_f32 v67, v67, v53, v86
	v_max3_f32 v68, v68, v88, v89
	v_max3_f32 v67, v67, v87, v54
	v_max3_f32 v68, v68, v56, v57
	v_max3_f32 v67, v67, v55, v90
	v_max3_f32 v68, v68, v92, v93
	v_max3_f32 v67, v67, v91, v58
	v_max3_f32 v68, v68, v60, v61
	v_max3_f32 v67, v67, v59, v94
	v_max3_f32 v68, v68, v96, v97
	v_max3_f32 v67, v67, v95, v62
	v_max3_f32 v68, v68, v64, v65
	v_add_f32_e32 v102, v190, v66
	v_max3_f32 v66, v67, v63, v68
	v_mov_b32_e32 v67, v66
	s_nop 1
	v_permlane32_swap_b32_e32 v66, v67
	v_max_f32_e32 v66, v66, v67
	v_cmp_lt_f32_e32 vcc, s48, v66
	s_cmp_lg_u64 vcc, 0
	s_cselect_b64 s[38:39], -1, 0
	s_cbranch_vccnz .LBB0_1321
